# states tile: two touch loads per thread (issued right after the dt loads) warm L2 with the tile's xBC rows so the conv-input loads after the dt phase hit closer; dt wait counts only the dt loads
# baseline (speedup 1.0000x reference)
.LBB0_1272:
	v_mov_b32_e32 v121, v252
	s_waitcnt vmcnt(63) expcnt(7) lgkmcnt(15)
	s_barrier
	s_load_dwordx2 s[4:5], s[0:1], 0x60
	s_load_dwordx2 s[98:99], s[0:1], 0x68
	s_add_i32 s9, s18, 0xfffffdd9
	v_readfirstlane_b32 s8, v121
	v_and_b32_e32 v140, 63, v121
	s_ashr_i32 s30, s8, 6
	s_lshl_b32 s10, s9, 6
	v_or_b32_e32 v0, s10, v140
	s_ashr_i32 s31, s30, 31
	v_lshlrev_b64 v[2:3], 5, v[0:1]
	s_lshl_b64 s[2:3], s[30:31], 2
	v_lshl_add_u64 v[2:3], s[12:13], 0, v[2:3]
	s_waitcnt lgkmcnt(0)
	s_add_u32 s4, s4, s2
	v_lshl_add_u64 v[2:3], v[2:3], 0, s[2:3]
	s_addc_u32 s5, s5, s3
	global_load_dword v0, v[2:3], off
	s_nop 0
	global_load_dword v2, v1, s[4:5]
	s_add_u32 s98, s98, s2
	s_addc_u32 s99, s99, s3
	global_load_dword v250, v1, s[98:99]
	v_readlane_b32 s100, v254, 32
	v_readlane_b32 s101, v254, 33
	s_add_i32 s32, s10, -3
	v_mul_u32_u24_e32 v186, 0x1556, v121
	v_add_u32_e32 v190, 0x200, v121
	v_lshrrev_b32_e32 v186, 16, v186
	v_mul_u32_u24_e32 v191, 0x1556, v190
	v_mul_u32_u24_e32 v187, 12, v186
	v_lshrrev_b32_e32 v191, 16, v191
	v_sub_u32_e32 v187, v121, v187
	v_mul_u32_u24_e32 v192, 12, v191
	v_add_u32_e32 v188, s32, v186
	v_sub_u32_e32 v192, v190, v192
	v_min_u32_e32 v191, 0x45, v191
	v_ashrrev_i32_e32 v189, 31, v188
	v_add_u32_e32 v194, s32, v191
	v_lshlrev_b64 v[188:189], 11, v[188:189]
	v_ashrrev_i32_e32 v195, 31, v194
	v_lshlrev_b32_e32 v187, 7, v187
	v_lshlrev_b64 v[194:195], 11, v[194:195]
	v_or_b32_e32 v188, v188, v187
	v_lshlrev_b32_e32 v192, 7, v192
	v_lshl_add_u64 v[188:189], s[100:101], 0, v[188:189]
	v_or_b32_e32 v194, v194, v192
	global_load_dword v186, v[188:189], off
	v_lshl_add_u64 v[194:195], s[100:101], 0, v[194:195]
	global_load_dword v190, v[194:195], off
	s_mov_b32 s4, 0x41a00000
	s_waitcnt vmcnt(2)
	v_add_f32_e32 v0, v0, v2
	v_cmp_nlt_f32_e32 vcc, s4, v0
	s_and_saveexec_b64 s[4:5], vcc
	s_cbranch_execz .LBB0_1274
	v_mul_f32_e32 v2, 0x3fb8aa3b, v0
	v_rndne_f32_e32 v3, v2
	s_mov_b32 s6, 0x3fb8aa3b
	v_sub_f32_e32 v4, v2, v3
	v_fma_f32 v2, v0, s6, -v2
	v_fmac_f32_e32 v2, 0x32a5705f, v0
	v_add_f32_e32 v2, v4, v2
	v_cvt_i32_f32_e32 v3, v3
	v_exp_f32_e32 v2, v2
	s_mov_b32 s6, 0xc2ce8ed0
	v_cmp_ngt_f32_e32 vcc, s6, v0
	s_mov_b32 s6, 0x3f2aaaab
	v_ldexp_f32 v2, v2, v3
	v_cndmask_b32_e32 v2, 0, v2, vcc
	v_cmp_nlt_f32_e32 vcc, s80, v0
	s_nop 1
	v_cndmask_b32_e32 v0, v183, v2, vcc
	v_add_f32_e32 v4, 1.0, v0
	v_add_f32_e32 v2, -1.0, v4
	v_sub_f32_e32 v3, v2, v4
	v_add_f32_e32 v3, 1.0, v3
	v_sub_f32_e32 v2, v0, v2
	v_add_f32_e32 v5, v2, v3
	v_frexp_mant_f32_e32 v6, v4
	v_cvt_f64_f32_e32 v[2:3], v4
	v_frexp_exp_i32_f64_e32 v2, v[2:3]
	v_cmp_gt_f32_e32 vcc, s6, v6
	s_mov_b32 s6, 0x3f317218
	s_nop 0
	v_subbrev_co_u32_e32 v10, vcc, 0, v2, vcc
	v_sub_u32_e32 v2, 0, v10
	v_ldexp_f32 v3, v4, v2
	v_add_f32_e32 v4, -1.0, v3
	v_add_f32_e32 v6, 1.0, v3
	v_ldexp_f32 v2, v5, v2
	v_add_f32_e32 v5, 1.0, v4
	v_add_f32_e32 v7, -1.0, v6
	v_sub_f32_e32 v5, v3, v5
	v_sub_f32_e32 v3, v3, v7
	v_add_f32_e32 v5, v2, v5
	v_add_f32_e32 v2, v2, v3
	v_add_f32_e32 v11, v6, v2
	v_rcp_f32_e32 v13, v11
	v_sub_f32_e32 v3, v6, v11
	v_add_f32_e32 v12, v2, v3
	v_add_f32_e32 v3, v4, v5
	v_mul_f32_e32 v15, v3, v13
	v_sub_f32_e32 v2, v4, v3
	v_mul_f32_e32 v4, v11, v15
	v_fma_f32 v6, v15, v11, -v4
	v_fmac_f32_e32 v6, v15, v12
	v_add_f32_e32 v14, v5, v2
	v_add_f32_e32 v2, v4, v6
	v_sub_f32_e32 v5, v3, v2
	v_pk_add_f32 v[8:9], v[2:3], v[4:5] neg_lo:[0,1] neg_hi:[0,1]
	v_mov_b32_e32 v7, v2
	v_pk_add_f32 v[2:3], v[8:9], v[6:7] neg_lo:[0,1] neg_hi:[0,1]
	s_nop 0
	v_add_f32_e32 v3, v14, v3
	v_add_f32_e32 v2, v2, v3
	v_add_f32_e32 v3, v5, v2
	v_mul_f32_e32 v14, v13, v3
	v_mul_f32_e32 v4, v11, v14
	v_fma_f32 v6, v14, v11, -v4
	v_fmac_f32_e32 v6, v14, v12
	v_sub_f32_e32 v5, v5, v3
	v_add_f32_e32 v11, v2, v5
	v_add_f32_e32 v2, v4, v6
	v_sub_f32_e32 v5, v3, v2
	v_pk_add_f32 v[8:9], v[2:3], v[4:5] neg_lo:[0,1] neg_hi:[0,1]
	v_mov_b32_e32 v7, v2
	v_pk_add_f32 v[2:3], v[8:9], v[6:7] neg_lo:[0,1] neg_hi:[0,1]
	s_nop 0
	v_add_f32_e32 v3, v11, v3
	v_add_f32_e32 v2, v2, v3
	v_add_f32_e32 v3, v15, v14
	v_add_f32_e32 v2, v5, v2
	v_sub_f32_e32 v4, v3, v15
	v_mul_f32_e32 v2, v13, v2
	v_sub_f32_e32 v4, v14, v4
	v_add_f32_e32 v4, v4, v2
	v_add_f32_e32 v6, v3, v4
	v_mul_f32_e32 v7, v6, v6
	v_fmamk_f32 v2, v7, 0x3e9b6dac, v178
	v_fmaak_f32 v165, v7, v2, 0x3f2aaada
	v_cvt_f32_i32_e32 v2, v10
	v_sub_f32_e32 v3, v6, v3
	v_sub_f32_e32 v3, v4, v3
	v_ldexp_f32 v8, v3, 1
	v_mul_f32_e32 v3, v6, v7
	v_ldexp_f32 v5, v6, 1
	v_pk_mul_f32 v[6:7], v[2:3], v[164:165]
	s_nop 0
	v_fma_f32 v4, v2, s6, -v6
	v_fmac_f32_e32 v4, 0xb102e308, v2
	v_pk_add_f32 v[2:3], v[6:7], v[4:5]
	s_mov_b32 s6, 0x7f800000
	v_sub_f32_e32 v5, v3, v5
	v_sub_f32_e32 v5, v7, v5
	v_add_f32_e32 v9, v8, v5
	v_mov_b32_e32 v8, v6
	v_pk_add_f32 v[6:7], v[2:3], v[6:7] neg_lo:[0,1] neg_hi:[0,1]
	v_pk_add_f32 v[10:11], v[2:3], v[8:9]
	v_mov_b32_e32 v5, v2
	v_mov_b32_e32 v7, v11
	v_pk_add_f32 v[12:13], v[4:5], v[6:7] neg_lo:[0,1] neg_hi:[0,1]
	v_pk_add_f32 v[4:5], v[4:5], v[6:7]
	v_mov_b32_e32 v8, v9
	v_pk_add_f32 v[6:7], v[4:5], v[2:3] op_sel:[1,0] op_sel_hi:[0,1] neg_lo:[0,1] neg_hi:[0,1]
	v_pk_add_f32 v[14:15], v[10:11], v[6:7] op_sel_hi:[1,0] neg_lo:[0,1] neg_hi:[0,1]
	v_mov_b32_e32 v10, v11
	v_mov_b32_e32 v11, v5
	v_pk_mov_b32 v[6:7], v[2:3], v[6:7] op_sel:[1,0]
	v_mov_b32_e32 v9, v2
	v_pk_add_f32 v[6:7], v[10:11], v[6:7] neg_lo:[0,1] neg_hi:[0,1]
	v_mov_b32_e32 v14, v12
	v_pk_add_f32 v[2:3], v[8:9], v[6:7] neg_lo:[0,1] neg_hi:[0,1]
	v_mov_b32_e32 v13, v5
	v_pk_add_f32 v[6:7], v[14:15], v[2:3]
	v_cmp_neq_f32_e32 vcc, s6, v0
	v_pk_add_f32 v[8:9], v[6:7], v[6:7] op_sel:[0,1] op_sel_hi:[1,0]
	s_mov_b32 s6, 0x33800000
	v_pk_add_f32 v[4:5], v[4:5], v[8:9] op_sel:[1,0] op_sel_hi:[0,1]
	v_mov_b32_e32 v7, v4
	v_pk_add_f32 v[10:11], v[6:7], v[12:13] neg_lo:[0,1] neg_hi:[0,1]
	v_mov_b32_e32 v3, v8
	v_sub_f32_e32 v5, v6, v10
	v_pk_add_f32 v[2:3], v[2:3], v[10:11] neg_lo:[0,1] neg_hi:[0,1]
	v_sub_f32_e32 v5, v12, v5
	v_add_f32_e32 v2, v2, v5
	v_add_f32_e32 v2, v2, v3
	v_add_f32_e32 v2, v4, v2
	v_cndmask_b32_e32 v2, v183, v2, vcc
	v_cmp_lt_f32_e64 vcc, |v0|, s6
	s_nop 1
	v_cndmask_b32_e32 v0, v2, v0, vcc
